# v44 + epilogue priorities: lead group raised to 2 after its align barrier, both reset at re-stagger, trailing group back to 1 (P1, P5)
# speedup vs baseline: 1.0065x; 1.0034x over previous
; #define PG8_STAGE(bufoff, gbase, voff) do { _Pragma("unroll") for (int _i = 0; _i < 2; ++_i) \
;         __builtin_amdgcn_global_load_lds((const __attribute__((address_space(1))) unsigned*)((const char*)(gbase) + (voff)[_i]), (LAS unsigned*)(lds + (bufoff) + ldsw + _i * 8192), 16, 0, 0); } while (0)
; #define PG8_LDA(dst, b, h) do { _Pragma("unroll") for (int m = 0; m < 4; ++m) _Pragma("unroll") for (int k = 0; k < 2; ++k) dst[m][k] = *(const LAS bf16x8*)(lds + PG8_SA(b, h) + aoff + m * 2048 + k * 1024); } while (0)
; #define PG8_LDB(dst, b, h) do { _Pragma("unroll") for (int n = 0; n < 2; ++n) _Pragma("unroll") for (int k = 0; k < 2; ++k) dst[n][k] = *(const LAS bf16x8*)(lds + PG8_SB(b, h) + boff + n * 2048 + k * 1024); } while (0)
; #define PG8_MMA(ai, bj, At, Bt) do { __builtin_amdgcn_s_setprio(1); _Pragma("unroll") for (int m = 0; m < 4; ++m) _Pragma("unroll") for (int n = 0; n < 2; ++n) _Pragma("unroll") for (int k = 0; k < 2; ++k) \
;         acc[ai][bj][m][n] = __builtin_amdgcn_mfma_f32_16x16x32_bf16(Bt[n][k], At[m][k], acc[ai][bj][m][n], 0, 0, 0); __builtin_amdgcn_s_setprio(0); } while (0)
; #define PG8_WAIT_V(n) asm volatile("s_waitcnt vmcnt(" #n ")" ::: "memory")
; #define PG8_WAIT_L(n) asm volatile("s_waitcnt lgkmcnt(" #n ")" ::: "memory")
; #define PG8_BAR __builtin_amdgcn_s_barrier()
; #define PG8_SCHED __builtin_amdgcn_sched_barrier(0)
; template <class Epi, class SchedT, bool ALIGN_EPI, bool SP2>
; __device__ __forceinline__ void gemm_phase(LAS unsigned char* lds, const int ldk, const int nt, const SchedT& S, const Epi& E) {
;     ...
;             PG8_LDB(B0, 0, 0); PG8_LDB(B1, 0, 1); PG8_SCHED; PG8_LDA(At, 0, 0); PG8_STAGE(PG8_SA(1, 1), a1 + hstep, voffA);
;             PG8_WAIT_V(8); PG8_WAIT_L(0); PG8_BAR; PG8_MMA(0, 0, At, B0); PG8_MMA(0, 1, At, B1); PG8_BAR; PG8_SCHED;
;             PG8_LDA(At, 0, 1); PG8_STAGE(PG8_SB(0, 0), b2, voffB); PG8_STAGE(PG8_SB(0, 1), b2 + hstepB, voffB); PG8_STAGE(PG8_SA(0, 0), a2, voffA);
;             PG8_WAIT_V(8); PG8_WAIT_L(0); PG8_BAR; PG8_MMA(1, 0, At, B0); PG8_MMA(1, 1, At, B1); PG8_BAR; PG8_SCHED;
.LBB0_123:
	s_add_u32 s12, s0, 0xfff80080
	s_addc_u32 s13, s1, -1
	s_add_i32 s34, 0, 0x10000
	s_cmp_eq_u32 s21, 28
	s_cselect_b32 s17, s61, s13
	s_cselect_b32 s16, s60, s12
	v_add_u32_e32 v0, s34, v212
	s_cselect_b32 s13, s31, s19
	s_cselect_b32 s12, s30, s18
	s_add_i32 s38, 0, 0x14000
	s_waitcnt lgkmcnt(0)
	ds_read_b128 v[132:135], v0
	ds_read_b128 v[136:139], v0 offset:1024
	ds_read_b128 v[140:143], v0 offset:2048
	ds_read_b128 v[144:147], v0 offset:3072
	v_add_u32_e32 v0, s38, v212
	ds_read_b128 v[148:151], v0
	ds_read_b128 v[152:155], v0 offset:1024
	ds_read_b128 v[184:187], v0 offset:2048
	ds_read_b128 v[188:191], v0 offset:3072
	v_lshl_add_u64 v[2:3], s[0:1], 0, v[180:181]
	s_add_i32 m0, s88, 0xc000
	ds_read_b128 v[192:195], v216
	ds_read_b128 v[196:199], v216 offset:1024
	ds_read_b128 v[200:203], v216 offset:2048
	ds_read_b128 v[204:207], v216 offset:3072
	ds_read_b128 v[218:221], v216 offset:4096
	ds_read_b128 v[222:225], v216 offset:5120
	ds_read_b128 v[226:229], v216 offset:6144
	ds_read_b128 v[230:233], v216 offset:7168
	global_load_lds_dwordx4 v[2:3], off
	v_lshl_add_u64 v[2:3], s[0:1], 0, v[182:183]
	s_add_i32 m0, s88, 0xe000
	s_nop 0
	global_load_lds_dwordx4 v[2:3], off
	s_waitcnt vmcnt(8)
	s_waitcnt lgkmcnt(0)
	s_barrier
	s_waitcnt lgkmcnt(0)
	v_mfma_f32_16x16x32_bf16 v[128:131], v[132:135], v[192:195], v[128:131]
	v_mfma_f32_16x16x32_bf16 v[124:127], v[140:143], v[192:195], v[124:127]
	v_mfma_f32_16x16x32_bf16 v[112:115], v[132:135], v[200:203], v[112:115]
	v_mfma_f32_16x16x32_bf16 v[108:111], v[140:143], v[200:203], v[108:111]
	v_mfma_f32_16x16x32_bf16 v[96:99], v[132:135], v[218:221], v[96:99]
	v_mfma_f32_16x16x32_bf16 v[92:95], v[140:143], v[218:221], v[92:95]
	v_mfma_f32_16x16x32_bf16 v[80:83], v[132:135], v[226:229], v[80:83]
	v_mfma_f32_16x16x32_bf16 v[76:79], v[140:143], v[226:229], v[76:79]
	v_mfma_f32_16x16x32_bf16 v[128:131], v[136:139], v[196:199], v[128:131]
	v_mfma_f32_16x16x32_bf16 v[124:127], v[144:147], v[196:199], v[124:127]
	v_mfma_f32_16x16x32_bf16 v[112:115], v[136:139], v[204:207], v[112:115]
	v_mfma_f32_16x16x32_bf16 v[108:111], v[144:147], v[204:207], v[108:111]
	v_mfma_f32_16x16x32_bf16 v[96:99], v[136:139], v[222:225], v[96:99]
	v_mfma_f32_16x16x32_bf16 v[92:95], v[144:147], v[222:225], v[92:95]
	v_mfma_f32_16x16x32_bf16 v[80:83], v[136:139], v[230:233], v[80:83]
	v_mfma_f32_16x16x32_bf16 v[76:79], v[144:147], v[230:233], v[76:79]
	v_mfma_f32_16x16x32_bf16 v[120:123], v[148:151], v[192:195], v[120:123]
	v_mfma_f32_16x16x32_bf16 v[116:119], v[184:187], v[192:195], v[116:119]
	v_mfma_f32_16x16x32_bf16 v[104:107], v[148:151], v[200:203], v[104:107]
	v_mfma_f32_16x16x32_bf16 v[100:103], v[184:187], v[200:203], v[100:103]
	v_mfma_f32_16x16x32_bf16 v[88:91], v[148:151], v[218:221], v[88:91]
	v_mfma_f32_16x16x32_bf16 v[84:87], v[184:187], v[218:221], v[84:87]
	v_mfma_f32_16x16x32_bf16 v[72:75], v[148:151], v[226:229], v[72:75]
	v_mfma_f32_16x16x32_bf16 v[68:71], v[184:187], v[226:229], v[68:71]
	v_mfma_f32_16x16x32_bf16 v[120:123], v[152:155], v[196:199], v[120:123]
	v_mfma_f32_16x16x32_bf16 v[116:119], v[188:191], v[196:199], v[116:119]
	v_mfma_f32_16x16x32_bf16 v[104:107], v[152:155], v[204:207], v[104:107]
	v_mfma_f32_16x16x32_bf16 v[100:103], v[188:191], v[204:207], v[100:103]
	v_mfma_f32_16x16x32_bf16 v[88:91], v[152:155], v[222:225], v[88:91]
	v_mfma_f32_16x16x32_bf16 v[84:87], v[188:191], v[222:225], v[84:87]
	v_mfma_f32_16x16x32_bf16 v[72:75], v[152:155], v[230:233], v[72:75]
	v_mfma_f32_16x16x32_bf16 v[68:71], v[188:191], v[230:233], v[68:71]
	s_barrier
	s_add_i32 s34, s34, s87
	v_lshl_add_u64 v[208:209], s[12:13], 0, v[158:159]
	s_mov_b32 m0, s34
	ds_read_b128 v[192:195], v216 offset:16384
	ds_read_b128 v[196:199], v216 offset:17408
	ds_read_b128 v[200:203], v216 offset:18432
	ds_read_b128 v[204:207], v216 offset:19456
	ds_read_b128 v[218:221], v216 offset:20480
	ds_read_b128 v[222:225], v216 offset:21504
	ds_read_b128 v[226:229], v216 offset:22528
	ds_read_b128 v[230:233], v216 offset:23552
	global_load_lds_dwordx4 v[208:209], off
	s_add_i32 m0, s34, 0x2000
	s_add_u32 s34, s12, 0x20000
	v_lshl_add_u64 v[234:235], s[12:13], 0, v[174:175]
	s_addc_u32 s35, s13, 0
	s_add_i32 s38, s38, s87
	global_load_lds_dwordx4 v[234:235], off
	v_lshl_add_u64 v[2:3], s[34:35], 0, v[158:159]
	s_mov_b32 m0, s38
	v_lshl_add_u64 v[236:237], s[16:17], 0, v[156:157]
	global_load_lds_dwordx4 v[2:3], off
	v_lshl_add_u64 v[2:3], s[34:35], 0, v[174:175]
	s_add_i32 m0, s38, 0x2000
	v_lshl_add_u64 v[238:239], s[16:17], 0, v[160:161]
	global_load_lds_dwordx4 v[2:3], off
	s_mov_b32 m0, s88
	s_nop 0
	global_load_lds_dwordx4 v[236:237], off
	s_mov_b32 m0, s89
	s_nop 0
	global_load_lds_dwordx4 v[238:239], off
	s_waitcnt vmcnt(8)
	s_waitcnt lgkmcnt(0)
	s_barrier
; #define PG8_STAGE(bufoff, gbase, voff) do { _Pragma("unroll") for (int _i = 0; _i < 2; ++_i) \
;         __builtin_amdgcn_global_load_lds((const __attribute__((address_space(1))) unsigned*)((const char*)(gbase) + (voff)[_i]), (LAS unsigned*)(lds + (bufoff) + ldsw + _i * 8192), 16, 0, 0); } while (0)
; #define PG8_LDA(dst, b, h) do { _Pragma("unroll") for (int m = 0; m < 4; ++m) _Pragma("unroll") for (int k = 0; k < 2; ++k) dst[m][k] = *(const LAS bf16x8*)(lds + PG8_SA(b, h) + aoff + m * 2048 + k * 1024); } while (0)
; #define PG8_LDB(dst, b, h) do { _Pragma("unroll") for (int n = 0; n < 2; ++n) _Pragma("unroll") for (int k = 0; k < 2; ++k) dst[n][k] = *(const LAS bf16x8*)(lds + PG8_SB(b, h) + boff + n * 2048 + k * 1024); } while (0)
; #define PG8_MMA(ai, bj, At, Bt) do { __builtin_amdgcn_s_setprio(1); _Pragma("unroll") for (int m = 0; m < 4; ++m) _Pragma("unroll") for (int n = 0; n < 2; ++n) _Pragma("unroll") for (int k = 0; k < 2; ++k) \
;         acc[ai][bj][m][n] = __builtin_amdgcn_mfma_f32_16x16x32_bf16(Bt[n][k], At[m][k], acc[ai][bj][m][n], 0, 0, 0); __builtin_amdgcn_s_setprio(0); } while (0)
; #define PG8_WAIT_V(n) asm volatile("s_waitcnt vmcnt(" #n ")" ::: "memory")
; #define PG8_WAIT_L(n) asm volatile("s_waitcnt lgkmcnt(" #n ")" ::: "memory")
; #define PG8_BAR __builtin_amdgcn_s_barrier()
; #define PG8_SCHED __builtin_amdgcn_sched_barrier(0)
; template <class Epi, class SchedT, bool ALIGN_EPI, bool SP2>
; __device__ __forceinline__ void gemm_phase(LAS unsigned char* lds, const int ldk, const int nt, const SchedT& S, const Epi& E) {
;     ...
;             PG8_WAIT_V(8); PG8_WAIT_L(0); PG8_BAR; PG8_MMA(1, 0, At, B0); PG8_MMA(1, 1, At, B1); PG8_BAR; PG8_SCHED;
;             PG8_LDB(B0, 1, 0); PG8_LDB(B1, 1, 1); PG8_SCHED; PG8_LDA(At, 1, 0); PG8_STAGE(PG8_SA(0, 1), a2 + hstep, voffA);
;             PG8_WAIT_V(8); PG8_WAIT_L(0); PG8_BAR; PG8_MMA(0, 0, At, B0); PG8_MMA(0, 1, At, B1); PG8_BAR; PG8_SCHED;
	s_waitcnt lgkmcnt(0)
	v_mfma_f32_16x16x32_bf16 v[64:67], v[132:135], v[192:195], v[64:67]
	v_mfma_f32_16x16x32_bf16 v[60:63], v[140:143], v[192:195], v[60:63]
	v_mfma_f32_16x16x32_bf16 v[48:51], v[132:135], v[200:203], v[48:51]
	v_mfma_f32_16x16x32_bf16 v[44:47], v[140:143], v[200:203], v[44:47]
	v_mfma_f32_16x16x32_bf16 v[32:35], v[132:135], v[218:221], v[32:35]
	v_mfma_f32_16x16x32_bf16 v[28:31], v[140:143], v[218:221], v[28:31]
	v_mfma_f32_16x16x32_bf16 v[16:19], v[132:135], v[226:229], v[16:19]
	v_mfma_f32_16x16x32_bf16 v[12:15], v[140:143], v[226:229], v[12:15]
	v_mfma_f32_16x16x32_bf16 v[64:67], v[136:139], v[196:199], v[64:67]
	v_mfma_f32_16x16x32_bf16 v[60:63], v[144:147], v[196:199], v[60:63]
	v_mfma_f32_16x16x32_bf16 v[48:51], v[136:139], v[204:207], v[48:51]
	v_mfma_f32_16x16x32_bf16 v[44:47], v[144:147], v[204:207], v[44:47]
	v_mfma_f32_16x16x32_bf16 v[32:35], v[136:139], v[222:225], v[32:35]
	v_mfma_f32_16x16x32_bf16 v[28:31], v[144:147], v[222:225], v[28:31]
	v_mfma_f32_16x16x32_bf16 v[16:19], v[136:139], v[230:233], v[16:19]
	v_mfma_f32_16x16x32_bf16 v[12:15], v[144:147], v[230:233], v[12:15]
	v_mfma_f32_16x16x32_bf16 v[56:59], v[148:151], v[192:195], v[56:59]
	v_mfma_f32_16x16x32_bf16 v[52:55], v[184:187], v[192:195], v[52:55]
	v_mfma_f32_16x16x32_bf16 v[40:43], v[148:151], v[200:203], v[40:43]
	v_mfma_f32_16x16x32_bf16 v[36:39], v[184:187], v[200:203], v[36:39]
	v_mfma_f32_16x16x32_bf16 v[24:27], v[148:151], v[218:221], v[24:27]
	v_mfma_f32_16x16x32_bf16 v[20:23], v[184:187], v[218:221], v[20:23]
	v_mfma_f32_16x16x32_bf16 v[8:11], v[148:151], v[226:229], v[8:11]
	v_mfma_f32_16x16x32_bf16 v[2:5], v[184:187], v[226:229], v[4:7]
	v_mfma_f32_16x16x32_bf16 v[56:59], v[152:155], v[196:199], v[56:59]
	v_mfma_f32_16x16x32_bf16 v[52:55], v[188:191], v[196:199], v[52:55]
	v_mfma_f32_16x16x32_bf16 v[40:43], v[152:155], v[204:207], v[40:43]
	v_mfma_f32_16x16x32_bf16 v[36:39], v[188:191], v[204:207], v[36:39]
	v_mfma_f32_16x16x32_bf16 v[24:27], v[152:155], v[222:225], v[24:27]
	v_mfma_f32_16x16x32_bf16 v[20:23], v[188:191], v[222:225], v[20:23]
	v_mfma_f32_16x16x32_bf16 v[8:11], v[152:155], v[230:233], v[8:11]
	v_mfma_f32_16x16x32_bf16 v[2:5], v[188:191], v[230:233], v[2:5]
	s_barrier
	s_add_i32 s34, 0, 0x18000
	v_add_u32_e32 v0, s34, v212
	s_add_i32 s35, 0, 0x1c000
	ds_read_b128 v[132:135], v0
	ds_read_b128 v[136:139], v0 offset:1024
	ds_read_b128 v[140:143], v0 offset:2048
	ds_read_b128 v[144:147], v0 offset:3072
	v_add_u32_e32 v0, s35, v212
	ds_read_b128 v[148:151], v0
	ds_read_b128 v[152:155], v0 offset:1024
	ds_read_b128 v[184:187], v0 offset:2048
	ds_read_b128 v[188:191], v0 offset:3072
	s_add_u32 s16, s16, 0x80000
	s_addc_u32 s17, s17, 0
	s_mov_b32 m0, s90
	v_lshl_add_u64 v[6:7], s[16:17], 0, v[156:157]
	ds_read_b128 v[192:195], v216 offset:32768
	ds_read_b128 v[196:199], v216 offset:33792
	ds_read_b128 v[200:203], v216 offset:34816
	ds_read_b128 v[204:207], v216 offset:35840
	ds_read_b128 v[218:221], v216 offset:36864
	ds_read_b128 v[222:225], v216 offset:37888
	ds_read_b128 v[226:229], v216 offset:38912
	ds_read_b128 v[230:233], v216 offset:39936
	global_load_lds_dwordx4 v[6:7], off
	v_lshl_add_u64 v[6:7], s[16:17], 0, v[160:161]
	s_mov_b32 m0, s91
	s_nop 0
	global_load_lds_dwordx4 v[6:7], off
	s_waitcnt vmcnt(8)
	s_waitcnt lgkmcnt(0)
	s_barrier
	s_waitcnt lgkmcnt(0)
	v_mfma_f32_16x16x32_bf16 v[128:131], v[132:135], v[192:195], v[128:131]
	v_mfma_f32_16x16x32_bf16 v[124:127], v[140:143], v[192:195], v[124:127]
	v_mfma_f32_16x16x32_bf16 v[112:115], v[132:135], v[200:203], v[112:115]
	v_mfma_f32_16x16x32_bf16 v[108:111], v[140:143], v[200:203], v[108:111]
	v_mfma_f32_16x16x32_bf16 v[96:99], v[132:135], v[218:221], v[96:99]
	v_mfma_f32_16x16x32_bf16 v[92:95], v[140:143], v[218:221], v[92:95]
	v_mfma_f32_16x16x32_bf16 v[80:83], v[132:135], v[226:229], v[80:83]
	v_mfma_f32_16x16x32_bf16 v[76:79], v[140:143], v[226:229], v[76:79]
	v_mfma_f32_16x16x32_bf16 v[128:131], v[136:139], v[196:199], v[128:131]
	v_mfma_f32_16x16x32_bf16 v[124:127], v[144:147], v[196:199], v[124:127]
	v_mfma_f32_16x16x32_bf16 v[112:115], v[136:139], v[204:207], v[112:115]
	v_mfma_f32_16x16x32_bf16 v[108:111], v[144:147], v[204:207], v[108:111]
	v_mfma_f32_16x16x32_bf16 v[96:99], v[136:139], v[222:225], v[96:99]
	v_mfma_f32_16x16x32_bf16 v[92:95], v[144:147], v[222:225], v[92:95]
	v_mfma_f32_16x16x32_bf16 v[80:83], v[136:139], v[230:233], v[80:83]
	v_mfma_f32_16x16x32_bf16 v[76:79], v[144:147], v[230:233], v[76:79]
	v_mfma_f32_16x16x32_bf16 v[120:123], v[148:151], v[192:195], v[120:123]
	v_mfma_f32_16x16x32_bf16 v[116:119], v[184:187], v[192:195], v[116:119]
	v_mfma_f32_16x16x32_bf16 v[104:107], v[148:151], v[200:203], v[104:107]
	v_mfma_f32_16x16x32_bf16 v[100:103], v[184:187], v[200:203], v[100:103]
	v_mfma_f32_16x16x32_bf16 v[88:91], v[148:151], v[218:221], v[88:91]
	v_mfma_f32_16x16x32_bf16 v[84:87], v[184:187], v[218:221], v[84:87]
	v_mfma_f32_16x16x32_bf16 v[72:75], v[148:151], v[226:229], v[72:75]
	v_mfma_f32_16x16x32_bf16 v[68:71], v[184:187], v[226:229], v[68:71]
	v_mfma_f32_16x16x32_bf16 v[120:123], v[152:155], v[196:199], v[120:123]
	v_mfma_f32_16x16x32_bf16 v[116:119], v[188:191], v[196:199], v[116:119]
	v_mfma_f32_16x16x32_bf16 v[104:107], v[152:155], v[204:207], v[104:107]
	v_mfma_f32_16x16x32_bf16 v[100:103], v[188:191], v[204:207], v[100:103]
	v_mfma_f32_16x16x32_bf16 v[88:91], v[152:155], v[222:225], v[88:91]
	v_mfma_f32_16x16x32_bf16 v[84:87], v[188:191], v[222:225], v[84:87]
	v_mfma_f32_16x16x32_bf16 v[72:75], v[152:155], v[230:233], v[72:75]
	v_mfma_f32_16x16x32_bf16 v[68:71], v[188:191], v[230:233], v[68:71]
	s_barrier
; #define PG8_STAGE(bufoff, gbase, voff) do { _Pragma("unroll") for (int _i = 0; _i < 2; ++_i) \
;         __builtin_amdgcn_global_load_lds((const __attribute__((address_space(1))) unsigned*)((const char*)(gbase) + (voff)[_i]), (LAS unsigned*)(lds + (bufoff) + ldsw + _i * 8192), 16, 0, 0); } while (0)
; #define PG8_LDA(dst, b, h) do { _Pragma("unroll") for (int m = 0; m < 4; ++m) _Pragma("unroll") for (int k = 0; k < 2; ++k) dst[m][k] = *(const LAS bf16x8*)(lds + PG8_SA(b, h) + aoff + m * 2048 + k * 1024); } while (0)
; #define PG8_MMA(ai, bj, At, Bt) do { __builtin_amdgcn_s_setprio(1); _Pragma("unroll") for (int m = 0; m < 4; ++m) _Pragma("unroll") for (int n = 0; n < 2; ++n) _Pragma("unroll") for (int k = 0; k < 2; ++k) \
;         acc[ai][bj][m][n] = __builtin_amdgcn_mfma_f32_16x16x32_bf16(Bt[n][k], At[m][k], acc[ai][bj][m][n], 0, 0, 0); __builtin_amdgcn_s_setprio(0); } while (0)
; #define PG8_WAIT_V(n) asm volatile("s_waitcnt vmcnt(" #n ")" ::: "memory")
; #define PG8_WAIT_L(n) asm volatile("s_waitcnt lgkmcnt(" #n ")" ::: "memory")
; #define PG8_BAR __builtin_amdgcn_s_barrier()
; #define PG8_SCHED __builtin_amdgcn_sched_barrier(0)
; template <class Epi, class SchedT, bool ALIGN_EPI, bool SP2>
; __device__ __forceinline__ void gemm_phase(LAS unsigned char* lds, const int ldk, const int nt, const SchedT& S, const Epi& E) {
;     ...
;             PG8_LDA(At, 1, 1); PG8_STAGE(PG8_SB(1, 0), b3, voffB); PG8_STAGE(PG8_SB(1, 1), b3 + hstepB, voffB); PG8_STAGE(PG8_SA(1, 0), a3, voffA);
;             PG8_WAIT_V(8); PG8_WAIT_L(0); PG8_BAR; PG8_MMA(1, 0, At, B0); PG8_MMA(1, 1, At, B1); PG8_BAR; PG8_SCHED;
;     ...
;         if constexpr (ALIGN_EPI) { if (wr == 0) PG8_BAR; }
	s_add_i32 s16, s34, s87
	v_lshl_add_u64 v[6:7], v[208:209], 0, s[24:25]
	s_mov_b32 m0, s16
	ds_read_b128 v[192:195], v216 offset:49152
	ds_read_b128 v[196:199], v216 offset:50176
	ds_read_b128 v[200:203], v216 offset:51200
	ds_read_b128 v[204:207], v216 offset:52224
	ds_read_b128 v[218:221], v216 offset:53248
	ds_read_b128 v[222:225], v216 offset:54272
	ds_read_b128 v[226:229], v216 offset:55296
	ds_read_b128 v[230:233], v216 offset:56320
	global_load_lds_dwordx4 v[6:7], off
	s_add_i32 m0, s16, 0x2000
	s_add_u32 s12, s12, 0x20080
	v_lshl_add_u64 v[6:7], v[234:235], 0, s[24:25]
	s_addc_u32 s13, s13, 0
	s_add_i32 s16, s35, s87
	global_load_lds_dwordx4 v[6:7], off
	v_lshl_add_u64 v[6:7], s[12:13], 0, v[158:159]
	s_mov_b32 m0, s16
	s_nop 0
	global_load_lds_dwordx4 v[6:7], off
	v_lshl_add_u64 v[6:7], s[12:13], 0, v[174:175]
	s_add_i32 m0, s16, 0x2000
	s_nop 0
	global_load_lds_dwordx4 v[6:7], off
	v_lshl_add_u64 v[6:7], v[236:237], 0, s[24:25]
	s_mov_b32 m0, s92
	s_nop 0
	global_load_lds_dwordx4 v[6:7], off
	v_lshl_add_u64 v[6:7], v[238:239], 0, s[24:25]
	s_mov_b32 m0, s93
	s_nop 0
	global_load_lds_dwordx4 v[6:7], off
	s_waitcnt vmcnt(8)
	s_waitcnt lgkmcnt(0)
	s_barrier
	s_waitcnt lgkmcnt(0)
	v_mfma_f32_16x16x32_bf16 v[64:67], v[132:135], v[192:195], v[64:67]
	v_mfma_f32_16x16x32_bf16 v[60:63], v[140:143], v[192:195], v[60:63]
	v_mfma_f32_16x16x32_bf16 v[48:51], v[132:135], v[200:203], v[48:51]
	v_mfma_f32_16x16x32_bf16 v[44:47], v[140:143], v[200:203], v[44:47]
	v_mfma_f32_16x16x32_bf16 v[32:35], v[132:135], v[218:221], v[32:35]
	v_mfma_f32_16x16x32_bf16 v[28:31], v[140:143], v[218:221], v[28:31]
	v_mfma_f32_16x16x32_bf16 v[16:19], v[132:135], v[226:229], v[16:19]
	v_mfma_f32_16x16x32_bf16 v[12:15], v[140:143], v[226:229], v[12:15]
	v_mfma_f32_16x16x32_bf16 v[64:67], v[136:139], v[196:199], v[64:67]
	v_mfma_f32_16x16x32_bf16 v[60:63], v[144:147], v[196:199], v[60:63]
	v_mfma_f32_16x16x32_bf16 v[48:51], v[136:139], v[204:207], v[48:51]
	v_mfma_f32_16x16x32_bf16 v[44:47], v[144:147], v[204:207], v[44:47]
	v_mfma_f32_16x16x32_bf16 v[32:35], v[136:139], v[222:225], v[32:35]
	v_mfma_f32_16x16x32_bf16 v[28:31], v[144:147], v[222:225], v[28:31]
	v_mfma_f32_16x16x32_bf16 v[16:19], v[136:139], v[230:233], v[16:19]
	v_mfma_f32_16x16x32_bf16 v[12:15], v[144:147], v[230:233], v[12:15]
	v_mfma_f32_16x16x32_bf16 v[56:59], v[148:151], v[192:195], v[56:59]
	v_mfma_f32_16x16x32_bf16 v[52:55], v[184:187], v[192:195], v[52:55]
	v_mfma_f32_16x16x32_bf16 v[40:43], v[148:151], v[200:203], v[40:43]
	v_mfma_f32_16x16x32_bf16 v[36:39], v[184:187], v[200:203], v[36:39]
	v_mfma_f32_16x16x32_bf16 v[24:27], v[148:151], v[218:221], v[24:27]
	v_mfma_f32_16x16x32_bf16 v[20:23], v[184:187], v[218:221], v[20:23]
	v_mfma_f32_16x16x32_bf16 v[6:9], v[148:151], v[226:229], v[8:11]
	v_mfma_f32_16x16x32_bf16 v[2:5], v[184:187], v[226:229], v[2:5]
	v_mfma_f32_16x16x32_bf16 v[56:59], v[152:155], v[196:199], v[56:59]
	v_mfma_f32_16x16x32_bf16 v[52:55], v[188:191], v[196:199], v[52:55]
	v_mfma_f32_16x16x32_bf16 v[40:43], v[152:155], v[204:207], v[40:43]
	v_mfma_f32_16x16x32_bf16 v[36:39], v[188:191], v[204:207], v[36:39]
	v_mfma_f32_16x16x32_bf16 v[24:27], v[152:155], v[222:225], v[24:27]
	v_mfma_f32_16x16x32_bf16 v[20:23], v[188:191], v[222:225], v[20:23]
	v_mfma_f32_16x16x32_bf16 v[8:11], v[152:155], v[230:233], v[6:9]
	v_mfma_f32_16x16x32_bf16 v[4:7], v[188:191], v[230:233], v[2:5]
	s_barrier
	s_add_i32 s21, s21, 2
	s_add_u32 s0, s0, 0x100
	s_addc_u32 s1, s1, 0
	s_add_u32 s18, s18, 0x100
	s_addc_u32 s19, s19, 0
	s_cmp_gt_u32 s21, 29
	s_cbranch_scc0 .LBB0_123
	s_and_b64 vcc, exec, s[58:59]
	s_cbranch_vccz .LBB0_126
	s_barrier
	s_setprio 2

; #define PG8_BAR __builtin_amdgcn_s_barrier()
; template <class Epi, class SchedT, bool ALIGN_EPI, bool SP2>
; __device__ __forceinline__ void gemm_phase(LAS unsigned char* lds, const int ldk, const int nt, const SchedT& S, const Epi& E) {
;     ...
;         if (!has_next) break;
;         if (!(SchedT::kMode == 2 && cur.kind == 0)) {
; #pragma unroll
;         for (int a = 0; a < 2; ++a)
; #pragma unroll
;             for (int b = 0; b < 2; ++b)
; #pragma unroll
;                 for (int m = 0; m < 4; ++m)
; #pragma unroll
;                     for (int n = 0; n < 2; ++n) acc[a][b][m][n] = (f32x4){0.f, 0.f, 0.f, 0.f};
;         }
;         cur = nxt; cA = nA; cB = nB; ++ui;
;         if constexpr (ALIGN_EPI) { if (wr == 1) PG8_BAR; }
.LBB0_199:
.LBB0_203:
.LBB0_204:
.LBB0_206:
.LBB0_207:
.LBB0_210:
.LBB0_212:
.LBB0_213:
.LBB0_214:
.LBB0_216:
.LBB0_217:
.LBB0_218:
.LBB0_219:
.LBB0_220:
.LBB0_221:
.LBB0_222:
.LBB0_226:
.LBB0_227:
.LBB0_229:
.LBB0_230:
.LBB0_233:
.LBB0_235:
.LBB0_236:
.LBB0_237:
.LBB0_240:
.LBB0_241:
.LBB0_242:
.LBB0_243:
.LBB0_244:
.LBB0_245:
.LBB0_246:
.LBB0_247:
.LBB0_249:
.LBB0_252:
.LBB0_253:
.LBB0_254:
.LBB0_256:
.LBB0_259:
.LBB0_260:
.LBB0_261:
.LBB0_263:
.LBB0_266:
.LBB0_267:
.LBB0_268:
.LBB0_270:
.LBB0_273:
.LBB0_274:
.LBB0_275:
.LBB0_277:
.LBB0_280:
.LBB0_281:
.LBB0_282:
.LBB0_284:
.LBB0_287:
.LBB0_288:
.LBB0_289:
.LBB0_291:
.LBB0_294:
.LBB0_295:
.LBB0_296:
.LBB0_298:
.LBB0_301:
.LBB0_302:
.LBB0_303:
.LBB0_305:
.LBB0_308:
.LBB0_309:
.LBB0_310:
.LBB0_312:
.LBB0_315:
.LBB0_316:
.LBB0_317:
.LBB0_319:
.LBB0_322:
.LBB0_323:
.LBB0_324:
.LBB0_326:
.LBB0_329:
.LBB0_330:
.LBB0_331:
.LBB0_333:
.LBB0_336:
.LBB0_337:
.LBB0_338:
.LBB0_340:
.LBB0_343:
.LBB0_344:
.LBB0_345:
.LBB0_347:
.LBB0_350:
.LBB0_351:
.LBB0_352:
.LBB0_354:
	s_and_b64 vcc, exec, s[36:37]
	s_mov_b64 s[0:1], -1
	s_cbranch_vccnz .LBB0_117
	s_setprio 0
	s_andn2_b64 vcc, exec, s[46:47]
	s_cbranch_vccnz .LBB0_116
	s_barrier
	s_setprio 1
	s_branch .LBB0_116

; #define PG8_STAGE(bufoff, gbase, voff) do { _Pragma("unroll") for (int _i = 0; _i < 2; ++_i) \
;         __builtin_amdgcn_global_load_lds((const __attribute__((address_space(1))) unsigned*)((const char*)(gbase) + (voff)[_i]), (LAS unsigned*)(lds + (bufoff) + ldsw + _i * 8192), 16, 0, 0); } while (0)
; #define PG8_LDA(dst, b, h) do { _Pragma("unroll") for (int m = 0; m < 4; ++m) _Pragma("unroll") for (int k = 0; k < 2; ++k) dst[m][k] = *(const LAS bf16x8*)(lds + PG8_SA(b, h) + aoff + m * 2048 + k * 1024); } while (0)
; #define PG8_LDB(dst, b, h) do { _Pragma("unroll") for (int n = 0; n < 2; ++n) _Pragma("unroll") for (int k = 0; k < 2; ++k) dst[n][k] = *(const LAS bf16x8*)(lds + PG8_SB(b, h) + boff + n * 2048 + k * 1024); } while (0)
; #define PG8_MMA(ai, bj, At, Bt) do { __builtin_amdgcn_s_setprio(1); _Pragma("unroll") for (int m = 0; m < 4; ++m) _Pragma("unroll") for (int n = 0; n < 2; ++n) _Pragma("unroll") for (int k = 0; k < 2; ++k) \
;         acc[ai][bj][m][n] = __builtin_amdgcn_mfma_f32_16x16x32_bf16(Bt[n][k], At[m][k], acc[ai][bj][m][n], 0, 0, 0); __builtin_amdgcn_s_setprio(0); } while (0)
; #define PG8_WAIT_V(n) asm volatile("s_waitcnt vmcnt(" #n ")" ::: "memory")
; #define PG8_WAIT_L(n) asm volatile("s_waitcnt lgkmcnt(" #n ")" ::: "memory")
; #define PG8_BAR __builtin_amdgcn_s_barrier()
; #define PG8_SCHED __builtin_amdgcn_sched_barrier(0)
; template <class Epi, class SchedT, bool ALIGN_EPI, bool SP2>
; __device__ __forceinline__ void gemm_phase(LAS unsigned char* lds, const int ldk, const int nt, const SchedT& S, const Epi& E) {
;     ...
;             PG8_LDB(B0, 0, 0); PG8_LDB(B1, 0, 1); PG8_SCHED; PG8_LDA(At, 0, 0); PG8_STAGE(PG8_SA(1, 1), a1 + hstep, voffA);
;             PG8_WAIT_V(8); PG8_WAIT_L(0); PG8_BAR; PG8_MMA(0, 0, At, B0); PG8_MMA(0, 1, At, B1); PG8_BAR; PG8_SCHED;
;             PG8_LDA(At, 0, 1); PG8_STAGE(PG8_SB(0, 0), b2, voffB); PG8_STAGE(PG8_SB(0, 1), b2 + hstepB, voffB); PG8_STAGE(PG8_SA(0, 0), a2, voffA);
;             PG8_WAIT_V(8); PG8_WAIT_L(0); PG8_BAR; PG8_MMA(1, 0, At, B0); PG8_MMA(1, 1, At, B1); PG8_BAR; PG8_SCHED;
.LBB0_752:
	s_add_u32 s36, s34, 0xfff80080
	s_addc_u32 s37, s35, -1
	s_add_i32 s61, 0, 0x10000
	s_cmp_eq_u32 s59, 28
	s_cselect_b32 vcc_hi, s1, s37
	s_cselect_b32 vcc_lo, s0, s36
	s_cselect_b32 s37, s63, s17
	s_cselect_b32 s36, s62, s13
	s_add_i32 s64, 0, 0x14000
	v_add_u32_e32 v142, s61, v248
	v_add_u32_e32 v182, s64, v248
	ds_read_b128 v[130:133], v142
	ds_read_b128 v[134:137], v142 offset:1024
	ds_read_b128 v[138:141], v142 offset:2048
	ds_read_b128 v[142:145], v142 offset:3072
	ds_read_b128 v[158:161], v182
	ds_read_b128 v[174:177], v182 offset:1024
	ds_read_b128 v[178:181], v182 offset:2048
	ds_read_b128 v[182:185], v182 offset:3072
	v_lshl_add_u64 v[218:219], s[34:35], 0, v[154:155]
	s_add_i32 m0, s85, 0xc000
	ds_read_b128 v[186:189], v251
	ds_read_b128 v[190:193], v251 offset:1024
	ds_read_b128 v[194:197], v251 offset:2048
	ds_read_b128 v[198:201], v251 offset:3072
	ds_read_b128 v[202:205], v251 offset:4096
	ds_read_b128 v[206:209], v251 offset:5120
	ds_read_b128 v[210:213], v251 offset:6144
	ds_read_b128 v[214:217], v251 offset:7168
	global_load_lds_dwordx4 v[218:219], off
	v_lshl_add_u64 v[218:219], s[34:35], 0, v[156:157]
	s_add_i32 m0, s85, 0xe000
	s_nop 0
	global_load_lds_dwordx4 v[218:219], off
	s_waitcnt vmcnt(8)
	s_waitcnt lgkmcnt(0)
	s_barrier
	s_waitcnt lgkmcnt(0)
	v_mfma_f32_16x16x32_bf16 v[126:129], v[130:133], v[186:189], v[126:129]
	v_mfma_f32_16x16x32_bf16 v[62:65], v[138:141], v[186:189], v[62:65]
	v_mfma_f32_16x16x32_bf16 v[118:121], v[130:133], v[194:197], v[118:121]
	v_mfma_f32_16x16x32_bf16 v[58:61], v[138:141], v[194:197], v[58:61]
	v_mfma_f32_16x16x32_bf16 v[110:113], v[130:133], v[202:205], v[110:113]
	v_mfma_f32_16x16x32_bf16 v[46:49], v[138:141], v[202:205], v[46:49]
	v_mfma_f32_16x16x32_bf16 v[106:109], v[130:133], v[210:213], v[106:109]
	v_mfma_f32_16x16x32_bf16 v[42:45], v[138:141], v[210:213], v[42:45]
	v_mfma_f32_16x16x32_bf16 v[126:129], v[134:137], v[190:193], v[126:129]
	v_mfma_f32_16x16x32_bf16 v[62:65], v[142:145], v[190:193], v[62:65]
	v_mfma_f32_16x16x32_bf16 v[118:121], v[134:137], v[198:201], v[118:121]
	v_mfma_f32_16x16x32_bf16 v[58:61], v[142:145], v[198:201], v[58:61]
	v_mfma_f32_16x16x32_bf16 v[110:113], v[134:137], v[206:209], v[110:113]
	v_mfma_f32_16x16x32_bf16 v[46:49], v[142:145], v[206:209], v[46:49]
	v_mfma_f32_16x16x32_bf16 v[106:109], v[134:137], v[214:217], v[106:109]
	v_mfma_f32_16x16x32_bf16 v[42:45], v[142:145], v[214:217], v[42:45]
	v_mfma_f32_16x16x32_bf16 v[122:125], v[158:161], v[186:189], v[122:125]
	v_mfma_f32_16x16x32_bf16 v[54:57], v[178:181], v[186:189], v[54:57]
	v_mfma_f32_16x16x32_bf16 v[114:117], v[158:161], v[194:197], v[114:117]
	v_mfma_f32_16x16x32_bf16 v[50:53], v[178:181], v[194:197], v[50:53]
	v_mfma_f32_16x16x32_bf16 v[102:105], v[158:161], v[202:205], v[102:105]
	v_mfma_f32_16x16x32_bf16 v[38:41], v[178:181], v[202:205], v[38:41]
	v_mfma_f32_16x16x32_bf16 v[98:101], v[158:161], v[210:213], v[98:101]
	v_mfma_f32_16x16x32_bf16 v[34:37], v[178:181], v[210:213], v[34:37]
	v_mfma_f32_16x16x32_bf16 v[122:125], v[174:177], v[190:193], v[122:125]
	v_mfma_f32_16x16x32_bf16 v[54:57], v[182:185], v[190:193], v[54:57]
	v_mfma_f32_16x16x32_bf16 v[114:117], v[174:177], v[198:201], v[114:117]
	v_mfma_f32_16x16x32_bf16 v[50:53], v[182:185], v[198:201], v[50:53]
	v_mfma_f32_16x16x32_bf16 v[102:105], v[174:177], v[206:209], v[102:105]
	v_mfma_f32_16x16x32_bf16 v[38:41], v[182:185], v[206:209], v[38:41]
	v_mfma_f32_16x16x32_bf16 v[98:101], v[174:177], v[214:217], v[98:101]
	v_mfma_f32_16x16x32_bf16 v[34:37], v[182:185], v[214:217], v[34:37]
	s_barrier
	s_add_i32 s61, s61, s84
	v_lshl_add_u64 v[218:219], s[36:37], 0, v[0:1]
	s_mov_b32 m0, s61
	ds_read_b128 v[186:189], v251 offset:16384
	ds_read_b128 v[190:193], v251 offset:17408
	ds_read_b128 v[194:197], v251 offset:18432
	ds_read_b128 v[198:201], v251 offset:19456
	ds_read_b128 v[202:205], v251 offset:20480
	ds_read_b128 v[206:209], v251 offset:21504
	ds_read_b128 v[210:213], v251 offset:22528
	ds_read_b128 v[214:217], v251 offset:23552
	global_load_lds_dwordx4 v[218:219], off
	s_add_i32 m0, s61, 0x2000
	s_add_u32 s94, s36, 0x20000
	v_lshl_add_u64 v[220:221], s[36:37], 0, v[150:151]
	s_addc_u32 s95, s37, 0
	s_add_i32 s61, s64, s84
	global_load_lds_dwordx4 v[220:221], off
	v_lshl_add_u64 v[222:223], s[94:95], 0, v[0:1]
	s_mov_b32 m0, s61
	v_lshl_add_u64 v[224:225], vcc, 0, v[148:149]
	global_load_lds_dwordx4 v[222:223], off
	v_lshl_add_u64 v[222:223], s[94:95], 0, v[150:151]
	s_add_i32 m0, s61, 0x2000
	s_nop 0
	global_load_lds_dwordx4 v[222:223], off
	v_lshl_add_u64 v[222:223], vcc, 0, v[146:147]
	s_mov_b32 m0, s85
	s_nop 0
	global_load_lds_dwordx4 v[222:223], off
	s_mov_b32 m0, s86
	s_nop 0
	global_load_lds_dwordx4 v[224:225], off
	s_waitcnt vmcnt(8)
	s_waitcnt lgkmcnt(0)
	s_barrier
; #define PG8_STAGE(bufoff, gbase, voff) do { _Pragma("unroll") for (int _i = 0; _i < 2; ++_i) \
;         __builtin_amdgcn_global_load_lds((const __attribute__((address_space(1))) unsigned*)((const char*)(gbase) + (voff)[_i]), (LAS unsigned*)(lds + (bufoff) + ldsw + _i * 8192), 16, 0, 0); } while (0)
; #define PG8_LDA(dst, b, h) do { _Pragma("unroll") for (int m = 0; m < 4; ++m) _Pragma("unroll") for (int k = 0; k < 2; ++k) dst[m][k] = *(const LAS bf16x8*)(lds + PG8_SA(b, h) + aoff + m * 2048 + k * 1024); } while (0)
; #define PG8_LDB(dst, b, h) do { _Pragma("unroll") for (int n = 0; n < 2; ++n) _Pragma("unroll") for (int k = 0; k < 2; ++k) dst[n][k] = *(const LAS bf16x8*)(lds + PG8_SB(b, h) + boff + n * 2048 + k * 1024); } while (0)
; #define PG8_MMA(ai, bj, At, Bt) do { __builtin_amdgcn_s_setprio(1); _Pragma("unroll") for (int m = 0; m < 4; ++m) _Pragma("unroll") for (int n = 0; n < 2; ++n) _Pragma("unroll") for (int k = 0; k < 2; ++k) \
;         acc[ai][bj][m][n] = __builtin_amdgcn_mfma_f32_16x16x32_bf16(Bt[n][k], At[m][k], acc[ai][bj][m][n], 0, 0, 0); __builtin_amdgcn_s_setprio(0); } while (0)
; #define PG8_WAIT_V(n) asm volatile("s_waitcnt vmcnt(" #n ")" ::: "memory")
; #define PG8_WAIT_L(n) asm volatile("s_waitcnt lgkmcnt(" #n ")" ::: "memory")
; #define PG8_BAR __builtin_amdgcn_s_barrier()
; #define PG8_SCHED __builtin_amdgcn_sched_barrier(0)
; template <class Epi, class SchedT, bool ALIGN_EPI, bool SP2>
; __device__ __forceinline__ void gemm_phase(LAS unsigned char* lds, const int ldk, const int nt, const SchedT& S, const Epi& E) {
;     ...
;             PG8_WAIT_V(8); PG8_WAIT_L(0); PG8_BAR; PG8_MMA(1, 0, At, B0); PG8_MMA(1, 1, At, B1); PG8_BAR; PG8_SCHED;
;             PG8_LDB(B0, 1, 0); PG8_LDB(B1, 1, 1); PG8_SCHED; PG8_LDA(At, 1, 0); PG8_STAGE(PG8_SA(0, 1), a2 + hstep, voffA);
;             PG8_WAIT_V(8); PG8_WAIT_L(0); PG8_BAR; PG8_MMA(0, 0, At, B0); PG8_MMA(0, 1, At, B1); PG8_BAR; PG8_SCHED;
	s_waitcnt lgkmcnt(0)
	v_mfma_f32_16x16x32_bf16 v[94:97], v[130:133], v[186:189], v[94:97]
	v_mfma_f32_16x16x32_bf16 v[30:33], v[138:141], v[186:189], v[30:33]
	v_mfma_f32_16x16x32_bf16 v[90:93], v[130:133], v[194:197], v[90:93]
	v_mfma_f32_16x16x32_bf16 v[26:29], v[138:141], v[194:197], v[26:29]
	v_mfma_f32_16x16x32_bf16 v[78:81], v[130:133], v[202:205], v[78:81]
	v_mfma_f32_16x16x32_bf16 v[14:17], v[138:141], v[202:205], v[14:17]
	v_mfma_f32_16x16x32_bf16 v[74:77], v[130:133], v[210:213], v[74:77]
	v_mfma_f32_16x16x32_bf16 v[10:13], v[138:141], v[210:213], v[10:13]
	v_mfma_f32_16x16x32_bf16 v[94:97], v[134:137], v[190:193], v[94:97]
	v_mfma_f32_16x16x32_bf16 v[30:33], v[142:145], v[190:193], v[30:33]
	v_mfma_f32_16x16x32_bf16 v[90:93], v[134:137], v[198:201], v[90:93]
	v_mfma_f32_16x16x32_bf16 v[26:29], v[142:145], v[198:201], v[26:29]
	v_mfma_f32_16x16x32_bf16 v[78:81], v[134:137], v[206:209], v[78:81]
	v_mfma_f32_16x16x32_bf16 v[14:17], v[142:145], v[206:209], v[14:17]
	v_mfma_f32_16x16x32_bf16 v[74:77], v[134:137], v[214:217], v[74:77]
	v_mfma_f32_16x16x32_bf16 v[10:13], v[142:145], v[214:217], v[10:13]
	v_mfma_f32_16x16x32_bf16 v[86:89], v[158:161], v[186:189], v[86:89]
	v_mfma_f32_16x16x32_bf16 v[22:25], v[178:181], v[186:189], v[22:25]
	v_mfma_f32_16x16x32_bf16 v[82:85], v[158:161], v[194:197], v[82:85]
	v_mfma_f32_16x16x32_bf16 v[18:21], v[178:181], v[194:197], v[18:21]
	v_mfma_f32_16x16x32_bf16 v[70:73], v[158:161], v[202:205], v[70:73]
	v_mfma_f32_16x16x32_bf16 v[6:9], v[178:181], v[202:205], v[6:9]
	v_mfma_f32_16x16x32_bf16 v[66:69], v[158:161], v[210:213], v[66:69]
	v_mfma_f32_16x16x32_bf16 v[2:5], v[178:181], v[210:213], v[2:5]
	v_mfma_f32_16x16x32_bf16 v[86:89], v[174:177], v[190:193], v[86:89]
	v_mfma_f32_16x16x32_bf16 v[22:25], v[182:185], v[190:193], v[22:25]
	v_mfma_f32_16x16x32_bf16 v[82:85], v[174:177], v[198:201], v[82:85]
	v_mfma_f32_16x16x32_bf16 v[18:21], v[182:185], v[198:201], v[18:21]
	v_mfma_f32_16x16x32_bf16 v[70:73], v[174:177], v[206:209], v[70:73]
	v_mfma_f32_16x16x32_bf16 v[6:9], v[182:185], v[206:209], v[6:9]
	v_mfma_f32_16x16x32_bf16 v[66:69], v[174:177], v[214:217], v[66:69]
	v_mfma_f32_16x16x32_bf16 v[2:5], v[182:185], v[214:217], v[2:5]
	s_barrier
	s_add_i32 s61, 0, 0x18000
	s_add_i32 s64, 0, 0x1c000
	v_add_u32_e32 v142, s61, v248
	v_add_u32_e32 v182, s64, v248
	ds_read_b128 v[130:133], v142
	ds_read_b128 v[134:137], v142 offset:1024
	ds_read_b128 v[138:141], v142 offset:2048
	ds_read_b128 v[142:145], v142 offset:3072
	ds_read_b128 v[158:161], v182
	ds_read_b128 v[174:177], v182 offset:1024
	ds_read_b128 v[178:181], v182 offset:2048
	ds_read_b128 v[182:185], v182 offset:3072
	s_add_u32 s94, vcc_lo, 0x80000
	s_addc_u32 s95, vcc_hi, 0
	s_mov_b32 m0, s87
	v_lshl_add_u64 v[226:227], s[94:95], 0, v[146:147]
	ds_read_b128 v[186:189], v251 offset:32768
	ds_read_b128 v[190:193], v251 offset:33792
	ds_read_b128 v[194:197], v251 offset:34816
	ds_read_b128 v[198:201], v251 offset:35840
	ds_read_b128 v[202:205], v251 offset:36864
	ds_read_b128 v[206:209], v251 offset:37888
	ds_read_b128 v[210:213], v251 offset:38912
	ds_read_b128 v[214:217], v251 offset:39936
	global_load_lds_dwordx4 v[226:227], off
	v_lshl_add_u64 v[226:227], s[94:95], 0, v[148:149]
	s_mov_b32 m0, s88
	s_nop 0
	global_load_lds_dwordx4 v[226:227], off
	s_waitcnt vmcnt(8)
	s_waitcnt lgkmcnt(0)
	s_barrier
	s_waitcnt lgkmcnt(0)
	v_mfma_f32_16x16x32_bf16 v[126:129], v[130:133], v[186:189], v[126:129]
	v_mfma_f32_16x16x32_bf16 v[62:65], v[138:141], v[186:189], v[62:65]
	v_mfma_f32_16x16x32_bf16 v[118:121], v[130:133], v[194:197], v[118:121]
	v_mfma_f32_16x16x32_bf16 v[58:61], v[138:141], v[194:197], v[58:61]
	v_mfma_f32_16x16x32_bf16 v[110:113], v[130:133], v[202:205], v[110:113]
	v_mfma_f32_16x16x32_bf16 v[46:49], v[138:141], v[202:205], v[46:49]
	v_mfma_f32_16x16x32_bf16 v[106:109], v[130:133], v[210:213], v[106:109]
	v_mfma_f32_16x16x32_bf16 v[42:45], v[138:141], v[210:213], v[42:45]
	v_mfma_f32_16x16x32_bf16 v[126:129], v[134:137], v[190:193], v[126:129]
	v_mfma_f32_16x16x32_bf16 v[62:65], v[142:145], v[190:193], v[62:65]
	v_mfma_f32_16x16x32_bf16 v[118:121], v[134:137], v[198:201], v[118:121]
	v_mfma_f32_16x16x32_bf16 v[58:61], v[142:145], v[198:201], v[58:61]
	v_mfma_f32_16x16x32_bf16 v[110:113], v[134:137], v[206:209], v[110:113]
	v_mfma_f32_16x16x32_bf16 v[46:49], v[142:145], v[206:209], v[46:49]
	v_mfma_f32_16x16x32_bf16 v[106:109], v[134:137], v[214:217], v[106:109]
	v_mfma_f32_16x16x32_bf16 v[42:45], v[142:145], v[214:217], v[42:45]
	v_mfma_f32_16x16x32_bf16 v[122:125], v[158:161], v[186:189], v[122:125]
	v_mfma_f32_16x16x32_bf16 v[54:57], v[178:181], v[186:189], v[54:57]
	v_mfma_f32_16x16x32_bf16 v[114:117], v[158:161], v[194:197], v[114:117]
	v_mfma_f32_16x16x32_bf16 v[50:53], v[178:181], v[194:197], v[50:53]
	v_mfma_f32_16x16x32_bf16 v[102:105], v[158:161], v[202:205], v[102:105]
	v_mfma_f32_16x16x32_bf16 v[38:41], v[178:181], v[202:205], v[38:41]
	v_mfma_f32_16x16x32_bf16 v[98:101], v[158:161], v[210:213], v[98:101]
	v_mfma_f32_16x16x32_bf16 v[34:37], v[178:181], v[210:213], v[34:37]
	v_mfma_f32_16x16x32_bf16 v[122:125], v[174:177], v[190:193], v[122:125]
	v_mfma_f32_16x16x32_bf16 v[54:57], v[182:185], v[190:193], v[54:57]
	v_mfma_f32_16x16x32_bf16 v[114:117], v[174:177], v[198:201], v[114:117]
	v_mfma_f32_16x16x32_bf16 v[50:53], v[182:185], v[198:201], v[50:53]
	v_mfma_f32_16x16x32_bf16 v[102:105], v[174:177], v[206:209], v[102:105]
	v_mfma_f32_16x16x32_bf16 v[38:41], v[182:185], v[206:209], v[38:41]
	v_mfma_f32_16x16x32_bf16 v[98:101], v[174:177], v[214:217], v[98:101]
	v_mfma_f32_16x16x32_bf16 v[34:37], v[182:185], v[214:217], v[34:37]
	s_barrier
; #define PG8_STAGE(bufoff, gbase, voff) do { _Pragma("unroll") for (int _i = 0; _i < 2; ++_i) \
;         __builtin_amdgcn_global_load_lds((const __attribute__((address_space(1))) unsigned*)((const char*)(gbase) + (voff)[_i]), (LAS unsigned*)(lds + (bufoff) + ldsw + _i * 8192), 16, 0, 0); } while (0)
; #define PG8_LDA(dst, b, h) do { _Pragma("unroll") for (int m = 0; m < 4; ++m) _Pragma("unroll") for (int k = 0; k < 2; ++k) dst[m][k] = *(const LAS bf16x8*)(lds + PG8_SA(b, h) + aoff + m * 2048 + k * 1024); } while (0)
; #define PG8_MMA(ai, bj, At, Bt) do { __builtin_amdgcn_s_setprio(1); _Pragma("unroll") for (int m = 0; m < 4; ++m) _Pragma("unroll") for (int n = 0; n < 2; ++n) _Pragma("unroll") for (int k = 0; k < 2; ++k) \
;         acc[ai][bj][m][n] = __builtin_amdgcn_mfma_f32_16x16x32_bf16(Bt[n][k], At[m][k], acc[ai][bj][m][n], 0, 0, 0); __builtin_amdgcn_s_setprio(0); } while (0)
; #define PG8_WAIT_V(n) asm volatile("s_waitcnt vmcnt(" #n ")" ::: "memory")
; #define PG8_WAIT_L(n) asm volatile("s_waitcnt lgkmcnt(" #n ")" ::: "memory")
; #define PG8_BAR __builtin_amdgcn_s_barrier()
; #define PG8_SCHED __builtin_amdgcn_sched_barrier(0)
; __device__ __forceinline__ float row_rstd(const float* ssp, int row, int fq) {
;     const f32x4 a = *(const f32x4*)(ssp + (size_t)row * 32 + 8 * fq), b = *(const f32x4*)(ssp + (size_t)row * 32 + 8 * fq + 4);
;     float s = ((a[0] + a[1]) + (a[2] + a[3])) + ((b[0] + b[1]) + (b[2] + b[3]));
;     s += __shfl_xor(s, 16); s += __shfl_xor(s, 32);
; template <class Epi, class SchedT, bool ALIGN_EPI, bool SP2>
; __device__ __forceinline__ void gemm_phase(LAS unsigned char* lds, const int ldk, const int nt, const SchedT& S, const Epi& E) {
;     ...
;             PG8_LDA(At, 1, 1); PG8_STAGE(PG8_SB(1, 0), b3, voffB); PG8_STAGE(PG8_SB(1, 1), b3 + hstepB, voffB); PG8_STAGE(PG8_SA(1, 0), a3, voffA);
;             PG8_WAIT_V(8); PG8_WAIT_L(0); PG8_BAR; PG8_MMA(1, 0, At, B0); PG8_MMA(1, 1, At, B1); PG8_BAR; PG8_SCHED;
	s_add_i32 s61, s61, s84
	v_lshl_add_u64 v[218:219], v[218:219], 0, s[24:25]
	s_mov_b32 m0, s61
	ds_read_b128 v[186:189], v251 offset:49152
	ds_read_b128 v[190:193], v251 offset:50176
	ds_read_b128 v[194:197], v251 offset:51200
	ds_read_b128 v[198:201], v251 offset:52224
	ds_read_b128 v[202:205], v251 offset:53248
	ds_read_b128 v[206:209], v251 offset:54272
	ds_read_b128 v[210:213], v251 offset:55296
	ds_read_b128 v[214:217], v251 offset:56320
	global_load_lds_dwordx4 v[218:219], off
	s_add_i32 m0, s61, 0x2000
	s_add_u32 s36, s36, 0x20080
	v_lshl_add_u64 v[218:219], v[220:221], 0, s[24:25]
	s_addc_u32 s37, s37, 0
	s_add_i32 s61, s64, s84
	global_load_lds_dwordx4 v[218:219], off
	v_lshl_add_u64 v[218:219], s[36:37], 0, v[0:1]
	s_mov_b32 m0, s61
	s_nop 0
	global_load_lds_dwordx4 v[218:219], off
	v_lshl_add_u64 v[218:219], s[36:37], 0, v[150:151]
	s_add_i32 m0, s61, 0x2000
	s_nop 0
	global_load_lds_dwordx4 v[218:219], off
	v_lshl_add_u64 v[218:219], v[222:223], 0, s[24:25]
	s_mov_b32 m0, s89
	s_nop 0
	global_load_lds_dwordx4 v[218:219], off
	v_lshl_add_u64 v[218:219], v[224:225], 0, s[24:25]
	s_mov_b32 m0, s90
	s_nop 0
	global_load_lds_dwordx4 v[218:219], off
	s_waitcnt vmcnt(8)
	s_waitcnt lgkmcnt(0)
	s_barrier
	s_waitcnt lgkmcnt(0)
	v_mfma_f32_16x16x32_bf16 v[94:97], v[130:133], v[186:189], v[94:97]
	v_mfma_f32_16x16x32_bf16 v[30:33], v[138:141], v[186:189], v[30:33]
	v_mfma_f32_16x16x32_bf16 v[90:93], v[130:133], v[194:197], v[90:93]
	v_mfma_f32_16x16x32_bf16 v[26:29], v[138:141], v[194:197], v[26:29]
	v_mfma_f32_16x16x32_bf16 v[78:81], v[130:133], v[202:205], v[78:81]
	v_mfma_f32_16x16x32_bf16 v[14:17], v[138:141], v[202:205], v[14:17]
	v_mfma_f32_16x16x32_bf16 v[74:77], v[130:133], v[210:213], v[74:77]
	v_mfma_f32_16x16x32_bf16 v[10:13], v[138:141], v[210:213], v[10:13]
	v_mfma_f32_16x16x32_bf16 v[94:97], v[134:137], v[190:193], v[94:97]
	v_mfma_f32_16x16x32_bf16 v[30:33], v[142:145], v[190:193], v[30:33]
	v_mfma_f32_16x16x32_bf16 v[90:93], v[134:137], v[198:201], v[90:93]
	v_mfma_f32_16x16x32_bf16 v[26:29], v[142:145], v[198:201], v[26:29]
	v_mfma_f32_16x16x32_bf16 v[78:81], v[134:137], v[206:209], v[78:81]
	v_mfma_f32_16x16x32_bf16 v[14:17], v[142:145], v[206:209], v[14:17]
	v_mfma_f32_16x16x32_bf16 v[74:77], v[134:137], v[214:217], v[74:77]
	v_mfma_f32_16x16x32_bf16 v[10:13], v[142:145], v[214:217], v[10:13]
	v_mfma_f32_16x16x32_bf16 v[86:89], v[158:161], v[186:189], v[86:89]
	v_mfma_f32_16x16x32_bf16 v[22:25], v[178:181], v[186:189], v[22:25]
	v_mfma_f32_16x16x32_bf16 v[82:85], v[158:161], v[194:197], v[82:85]
	v_mfma_f32_16x16x32_bf16 v[18:21], v[178:181], v[194:197], v[18:21]
	v_mfma_f32_16x16x32_bf16 v[70:73], v[158:161], v[202:205], v[70:73]
	v_mfma_f32_16x16x32_bf16 v[6:9], v[178:181], v[202:205], v[6:9]
	v_mfma_f32_16x16x32_bf16 v[66:69], v[158:161], v[210:213], v[66:69]
	v_mfma_f32_16x16x32_bf16 v[2:5], v[178:181], v[210:213], v[2:5]
	v_mfma_f32_16x16x32_bf16 v[86:89], v[174:177], v[190:193], v[86:89]
	v_mfma_f32_16x16x32_bf16 v[22:25], v[182:185], v[190:193], v[22:25]
	v_mfma_f32_16x16x32_bf16 v[82:85], v[174:177], v[198:201], v[82:85]
	v_mfma_f32_16x16x32_bf16 v[18:21], v[182:185], v[198:201], v[18:21]
	v_mfma_f32_16x16x32_bf16 v[70:73], v[174:177], v[206:209], v[70:73]
	v_mfma_f32_16x16x32_bf16 v[6:9], v[182:185], v[206:209], v[6:9]
	v_mfma_f32_16x16x32_bf16 v[66:69], v[174:177], v[214:217], v[66:69]
	v_mfma_f32_16x16x32_bf16 v[2:5], v[182:185], v[214:217], v[2:5]
	s_barrier
	s_add_i32 s59, s59, 2
	s_add_u32 s34, s34, 0x100
	s_addc_u32 s35, s35, 0
	s_add_u32 s13, s13, 0x100
	s_addc_u32 s17, s17, 0
	s_cmp_gt_u32 s59, 29
	s_cbranch_scc0 .LBB0_752
	v_lshl_add_u32 v130, s12, 8, v247
	v_lshlrev_b32_e32 v140, 7, v130
	v_mov_b32_e32 v141, 0
	v_lshl_add_u64 v[132:133], v[152:153], 0, v[140:141]
	v_add_u32_e32 v140, 0x1000, v140
	v_lshl_add_u64 v[134:135], v[152:153], 0, v[140:141]
	v_add_u32_e32 v140, 0x3000, v140
	v_lshl_add_u64 v[136:137], v[152:153], 0, v[140:141]
	v_add_u32_e32 v140, 0x1000, v140
	v_lshl_add_u64 v[138:139], v[152:153], 0, v[140:141]
	global_load_dwordx4 v[174:177], v[132:133], off
	global_load_dwordx4 v[178:181], v[132:133], off offset:16
	global_load_dwordx4 v[182:185], v[132:133], off offset:2048
	global_load_dwordx4 v[186:189], v[132:133], off offset:2064
	global_load_dwordx4 v[190:193], v[134:135], off
	global_load_dwordx4 v[194:197], v[134:135], off offset:16
	global_load_dwordx4 v[198:201], v[134:135], off offset:2048
	global_load_dwordx4 v[202:205], v[134:135], off offset:2064
	global_load_dwordx4 v[206:209], v[136:137], off
	global_load_dwordx4 v[210:213], v[136:137], off offset:16
	global_load_dwordx4 v[214:217], v[136:137], off offset:2048
	global_load_dwordx4 v[218:221], v[136:137], off offset:2064
	global_load_dwordx4 v[222:225], v[138:139], off
	global_load_dwordx4 v[226:229], v[138:139], off offset:16
	global_load_dwordx4 v[230:233], v[138:139], off offset:2048
	global_load_dwordx4 v[234:237], v[138:139], off offset:2064
	v_xor_b32_e32 v238, 16, v241
	v_xor_b32_e32 v239, 32, v241
	v_lshlrev_b32_e32 v238, 2, v238
	v_lshlrev_b32_e32 v239, 2, v239
	s_and_b64 vcc, exec, s[56:57]
	s_cbranch_vccz .LBB0_755
	s_barrier
	s_setprio 2

; #define PG8_BAR __builtin_amdgcn_s_barrier()
; template <class Epi, class SchedT, bool ALIGN_EPI, bool SP2>
; __device__ __forceinline__ void gemm_phase(LAS unsigned char* lds, const int ldk, const int nt, const SchedT& S, const Epi& E) {
;     ...
;         cur = nxt; cA = nA; cB = nB; ++ui;
;         if constexpr (ALIGN_EPI) { if (wr == 1) PG8_BAR; }
.LBB0_788:
	s_setprio 0
	s_andn2_b64 vcc, exec, s[52:53]
	s_cbranch_vccnz .LBB0_745
	s_barrier
	s_setprio 1
	s_branch .LBB0_745
